# diff flash loop: V fragments prefetched 4 deep, exp/cvt interleaved with PV MFMAs, negm used directly as QK C operand
# speedup vs baseline: 1.0161x; 1.0161x over previous
; #define MFMA(a, b, c) __builtin_amdgcn_mfma_f32_32x32x16_bf16((a), (b), (c), 0, 0, 0)
; template <int DQK, int DV, int NKH, int MODE>
; DEV void flash_unit(const FlashArgs& fa, char* smem, f32x16 (&oacc)[DV / 32], float& linv_out) {
;     ...
;       for (int k2 = 0; k2 < 2; ++k2) {
; #pragma unroll
;         for (int s = 0; s < NS; ++s) {
;           const bf16x8 kf = kfr[k2][s];
;           if (s == 0) st[k2] = MFMA(kf, qf[s], negm);
;           else st[k2] = MFMA(kf, qf[s], st[k2]);
;           constexpr int NQK = 2 * NS, EVERY = NQK / LPT;
;           const int m = k2 * NS + s;
;           if ((m + 1) % EVERY == 0 && (m + 1) / EVERY <= LPT) {
;             __builtin_amdgcn_sched_barrier(0);
;             if (pre) issue_piece(it + 3, (m + 1) / EVERY - 1);
;             __builtin_amdgcn_sched_barrier(0);
;           }
;         }
;       }
.LBB0_84:
	v_mfma_f32_32x32x16_bf16 v[80:95], v[136:139], v[120:123], v[64:79]
	v_mfma_f32_32x32x16_bf16 v[80:95], v[140:143], v[112:115], v[80:95]
	s_and_b64 vcc, exec, s[0:1]
	s_cbranch_vccnz .LBB0_86
	v_add_u32_e32 v136, 0x4000, v144
	s_nop 0
	v_readfirstlane_b32 s2, v136
	s_mov_b32 m0, s2
	s_nop 0
	global_load_lds_dwordx4 v[160:161], off

; DEV float fast_exp2(float x) { return __builtin_amdgcn_exp2f(x); }
; template <int DQK, int DV, int NKH, int MODE>
; DEV void flash_unit(const FlashArgs& fa, char* smem, f32x16 (&oacc)[DV / 32], float& linv_out) {
;     ...
;       float rel = st[0][0];
; #pragma unroll
;       for (int e = 1; e < 16; ++e) rel = fmaxf(rel, st[0][e]);
; #pragma unroll
;       for (int e = 0; e < 16; ++e) rel = fmaxf(rel, st[1][e]);
;       rel = half_max(rel);
;       const bool first = (it == 0);
;       if (first || __builtin_amdgcn_ballot_w64(rel > 8.f) != 0) {
;         const float d = first ? rel : fmaxf(rel, 0.f);
;         const float alpha = fast_exp2(-d);
;         mrun += d;
; #pragma unroll
;         for (int k2 = 0; k2 < 2; ++k2)
; #pragma unroll
;           for (int e = 0; e < 16; ++e) st[k2][e] -= d;
; #pragma unroll
;         for (int v = 0; v < NV; ++v)
; #pragma unroll
;           for (int e = 0; e < 16; ++e) oacc[v][e] *= alpha;
; #pragma unroll
;         for (int e = 0; e < 16; ++e) negm[e] = -mrun;
;         lrun *= alpha;
;       }
;     ...
;             const char* a1 = vb + (k2 * 32 + s2 * 16) * VROW + vhi[v] + vlow0;
;             const char* a2 = vb + (k2 * 32 + s2 * 16 + 8) * VROW + vhi[v] + vlow1;
;             s16x4 lo = __builtin_amdgcn_ds_read_tr16_b64_v4i16((__attribute__((address_space(3))) s16x4*)(a1));
;             s16x4 hi = __builtin_amdgcn_ds_read_tr16_b64_v4i16((__attribute__((address_space(3))) s16x4*)(a2));
.LBB0_88:
	v_add3_u32 v251, v194, v195, v196
	v_add3_u32 v252, v194, v197, v196
	v_add3_u32 v243, s16, v188, v251
	v_add3_u32 v244, s16, v188, v252
	v_add3_u32 v245, s16, v189, v251
	v_add3_u32 v246, s16, v189, v252
	v_add3_u32 v247, s16, v190, v251
	v_add3_u32 v248, s16, v190, v252
	v_add3_u32 v249, s16, v191, v251
	v_add3_u32 v250, s16, v191, v252
	ds_read_b64_tr_b16 v[128:129], v243 offset:16384
	ds_read_b64_tr_b16 v[130:131], v244 offset:18432
	ds_read_b64_tr_b16 v[132:133], v245 offset:16384
	ds_read_b64_tr_b16 v[134:135], v246 offset:18432
	ds_read_b64_tr_b16 v[136:137], v247 offset:16384
	ds_read_b64_tr_b16 v[138:139], v248 offset:18432
	ds_read_b64_tr_b16 v[140:141], v249 offset:16384
	ds_read_b64_tr_b16 v[142:143], v250 offset:18432
	v_max3_f32 v144, v96, v97, v98
	v_max3_f32 v144, v144, v99, v100
	v_max3_f32 v144, v144, v101, v102
	v_max3_f32 v144, v144, v103, v104
	v_max3_f32 v144, v144, v105, v106
	v_max3_f32 v144, v144, v107, v108
	v_max3_f32 v144, v144, v109, v110
	v_max3_f32 v144, v144, v111, v80
	v_max3_f32 v144, v144, v81, v82
	v_max3_f32 v144, v144, v83, v84
	v_max3_f32 v144, v144, v85, v86
	v_max3_f32 v144, v144, v87, v88
	v_max3_f32 v144, v144, v89, v90
	v_max3_f32 v144, v144, v91, v92
	v_max3_f32 v144, v144, v93, v94
	v_max_f32_e32 v144, v144, v95
	v_mov_b32_e32 v251, v144
	s_nop 1
	v_permlane32_swap_b32_e32 v144, v251
	v_max_f32_e32 v144, v144, v251
	v_cmp_lt_f32_e32 vcc, s33, v144
	s_cbranch_vccz .LBB0_90
	v_max_f32_e32 v64, v144, v144
	v_max_f32_e32 v64, 0, v64
	v_exp_f32_e64 v66, -v64
	v_add_f32_e32 v157, v157, v64
	v_pk_add_f32 v[96:97], v[96:97], v[64:65] op_sel_hi:[1,0] neg_lo:[0,1] neg_hi:[0,1]
	v_pk_add_f32 v[98:99], v[98:99], v[64:65] op_sel_hi:[1,0] neg_lo:[0,1] neg_hi:[0,1]
	v_pk_add_f32 v[100:101], v[100:101], v[64:65] op_sel_hi:[1,0] neg_lo:[0,1] neg_hi:[0,1]
	v_pk_add_f32 v[102:103], v[102:103], v[64:65] op_sel_hi:[1,0] neg_lo:[0,1] neg_hi:[0,1]
	v_pk_add_f32 v[104:105], v[104:105], v[64:65] op_sel_hi:[1,0] neg_lo:[0,1] neg_hi:[0,1]
	v_pk_add_f32 v[106:107], v[106:107], v[64:65] op_sel_hi:[1,0] neg_lo:[0,1] neg_hi:[0,1]
	v_pk_add_f32 v[108:109], v[108:109], v[64:65] op_sel_hi:[1,0] neg_lo:[0,1] neg_hi:[0,1]
	v_pk_add_f32 v[110:111], v[110:111], v[64:65] op_sel_hi:[1,0] neg_lo:[0,1] neg_hi:[0,1]
	v_pk_add_f32 v[80:81], v[80:81], v[64:65] op_sel_hi:[1,0] neg_lo:[0,1] neg_hi:[0,1]
	v_pk_add_f32 v[82:83], v[82:83], v[64:65] op_sel_hi:[1,0] neg_lo:[0,1] neg_hi:[0,1]
	v_pk_add_f32 v[84:85], v[84:85], v[64:65] op_sel_hi:[1,0] neg_lo:[0,1] neg_hi:[0,1]
	v_pk_add_f32 v[86:87], v[86:87], v[64:65] op_sel_hi:[1,0] neg_lo:[0,1] neg_hi:[0,1]
	v_pk_add_f32 v[88:89], v[88:89], v[64:65] op_sel_hi:[1,0] neg_lo:[0,1] neg_hi:[0,1]
	v_pk_add_f32 v[90:91], v[90:91], v[64:65] op_sel_hi:[1,0] neg_lo:[0,1] neg_hi:[0,1]
	v_pk_add_f32 v[92:93], v[92:93], v[64:65] op_sel_hi:[1,0] neg_lo:[0,1] neg_hi:[0,1]
	v_pk_add_f32 v[94:95], v[94:95], v[64:65] op_sel_hi:[1,0] neg_lo:[0,1] neg_hi:[0,1]
	v_xor_b32_e32 v64, 0x80000000, v157
	v_pk_mul_f32 v[46:47], v[46:47], v[66:67] op_sel_hi:[1,0]
	v_pk_mul_f32 v[44:45], v[44:45], v[66:67] op_sel_hi:[1,0]
	v_pk_mul_f32 v[42:43], v[42:43], v[66:67] op_sel_hi:[1,0]
	v_pk_mul_f32 v[40:41], v[40:41], v[66:67] op_sel_hi:[1,0]
	v_pk_mul_f32 v[38:39], v[38:39], v[66:67] op_sel_hi:[1,0]
	v_pk_mul_f32 v[36:37], v[36:37], v[66:67] op_sel_hi:[1,0]
	v_pk_mul_f32 v[34:35], v[34:35], v[66:67] op_sel_hi:[1,0]
	v_pk_mul_f32 v[32:33], v[32:33], v[66:67] op_sel_hi:[1,0]
	v_pk_mul_f32 v[62:63], v[62:63], v[66:67] op_sel_hi:[1,0]
	v_pk_mul_f32 v[60:61], v[60:61], v[66:67] op_sel_hi:[1,0]
	v_pk_mul_f32 v[58:59], v[58:59], v[66:67] op_sel_hi:[1,0]
	v_pk_mul_f32 v[56:57], v[56:57], v[66:67] op_sel_hi:[1,0]
	v_pk_mul_f32 v[54:55], v[54:55], v[66:67] op_sel_hi:[1,0]
	v_pk_mul_f32 v[52:53], v[52:53], v[66:67] op_sel_hi:[1,0]
	v_pk_mul_f32 v[50:51], v[50:51], v[66:67] op_sel_hi:[1,0]
	v_pk_mul_f32 v[48:49], v[48:49], v[66:67] op_sel_hi:[1,0]
	v_pk_mul_f32 v[30:31], v[30:31], v[66:67] op_sel_hi:[1,0]
	v_pk_mul_f32 v[28:29], v[28:29], v[66:67] op_sel_hi:[1,0]
	v_pk_mul_f32 v[26:27], v[26:27], v[66:67] op_sel_hi:[1,0]
	v_pk_mul_f32 v[24:25], v[24:25], v[66:67] op_sel_hi:[1,0]
	v_pk_mul_f32 v[22:23], v[22:23], v[66:67] op_sel_hi:[1,0]
	v_pk_mul_f32 v[20:21], v[20:21], v[66:67] op_sel_hi:[1,0]
	v_pk_mul_f32 v[18:19], v[18:19], v[66:67] op_sel_hi:[1,0]
	v_pk_mul_f32 v[16:17], v[16:17], v[66:67] op_sel_hi:[1,0]
	v_pk_mul_f32 v[14:15], v[14:15], v[66:67] op_sel_hi:[1,0]
	v_pk_mul_f32 v[12:13], v[12:13], v[66:67] op_sel_hi:[1,0]
	v_pk_mul_f32 v[10:11], v[10:11], v[66:67] op_sel_hi:[1,0]
	v_pk_mul_f32 v[8:9], v[8:9], v[66:67] op_sel_hi:[1,0]
	v_pk_mul_f32 v[6:7], v[6:7], v[66:67] op_sel_hi:[1,0]
	v_pk_mul_f32 v[4:5], v[4:5], v[66:67] op_sel_hi:[1,0]
	v_pk_mul_f32 v[2:3], v[2:3], v[66:67] op_sel_hi:[1,0]
	v_pk_mul_f32 v[0:1], v[0:1], v[66:67] op_sel_hi:[1,0]
	v_mul_f32_e32 v156, v156, v66
	v_mov_b32_e32 v65, v64
	v_mov_b32_e32 v66, v64
	v_mov_b32_e32 v67, v64
	v_mov_b32_e32 v68, v64
	v_mov_b32_e32 v69, v64
	v_mov_b32_e32 v70, v64
	v_mov_b32_e32 v71, v64
	v_mov_b32_e32 v72, v64
	v_mov_b32_e32 v73, v64
	v_mov_b32_e32 v74, v64
	v_mov_b32_e32 v75, v64
	v_mov_b32_e32 v76, v64
	v_mov_b32_e32 v77, v64
	v_mov_b32_e32 v78, v64
	v_mov_b32_e32 v79, v64
; #define MFMA(a, b, c) __builtin_amdgcn_mfma_f32_32x32x16_bf16((a), (b), (c), 0, 0, 0)
; DEV float fast_exp2(float x) { return __builtin_amdgcn_exp2f(x); }
; template <int DQK, int DV, int NKH, int MODE>
; DEV void flash_unit(const FlashArgs& fa, char* smem, f32x16 (&oacc)[DV / 32], float& linv_out) {
;     ...
;       float psum = 0.f;
; #pragma unroll
;       for (int k2 = 0; k2 < 2; ++k2)
; #pragma unroll
;         for (int e = 0; e < 16; ++e) { st[k2][e] = fast_exp2(st[k2][e]); psum += st[k2][e]; }
;       lrun += psum;
;       bf16x8 pf[2][2];
; #pragma unroll
;       for (int k2 = 0; k2 < 2; ++k2)
; #pragma unroll
;         for (int s2 = 0; s2 < 2; ++s2) {
;           uint4 u = make_uint4(pk2(st[k2][8 * s2], st[k2][8 * s2 + 1]), pk2(st[k2][8 * s2 + 2], st[k2][8 * s2 + 3]),
;                                pk2(st[k2][8 * s2 + 4], st[k2][8 * s2 + 5]), pk2(st[k2][8 * s2 + 6], st[k2][8 * s2 + 7]));
;           pf[k2][s2] = __builtin_bit_cast(bf16x8, u);
;         }
; #pragma unroll
;       for (int v = 0; v < NV; ++v)
; #pragma unroll
;         for (int k2 = 0; k2 < 2; ++k2)
; #pragma unroll
;           for (int s2 = 0; s2 < 2; ++s2) {
;             const char* a1 = vb + (k2 * 32 + s2 * 16) * VROW + vhi[v] + vlow0;
;             const char* a2 = vb + (k2 * 32 + s2 * 16 + 8) * VROW + vhi[v] + vlow1;
;             s16x4 lo = __builtin_amdgcn_ds_read_tr16_b64_v4i16((__attribute__((address_space(3))) s16x4*)(a1));
;             s16x4 hi = __builtin_amdgcn_ds_read_tr16_b64_v4i16((__attribute__((address_space(3))) s16x4*)(a2));
;             const bf16x8 vf = __builtin_shufflevector(lo, hi, 0, 1, 2, 3, 4, 5, 6, 7);
;             oacc[v] = MFMA(vf, pf[k2][s2], oacc[v]);
;           }
.LBB0_90:
	v_exp_f32_e32 v96, v96
	v_exp_f32_e32 v97, v97
	v_exp_f32_e32 v98, v98
	v_exp_f32_e32 v99, v99
	v_add_f32_e32 v253, v96, v97
	v_exp_f32_e32 v100, v100
	v_cvt_pk_bf16_f32 v96, v96, v97
	v_exp_f32_e32 v101, v101
	v_add_f32_e32 v253, v253, v98
	v_exp_f32_e32 v102, v102
	v_add_f32_e32 v253, v253, v99
	v_exp_f32_e32 v103, v103
	v_cvt_pk_bf16_f32 v97, v98, v99
	v_add_f32_e32 v253, v253, v100
	v_cvt_pk_bf16_f32 v98, v100, v101
	v_add_f32_e32 v253, v253, v101
	v_cvt_pk_bf16_f32 v99, v102, v103
	v_add_f32_e32 v253, v253, v102
	v_add_f32_e32 v253, v253, v103
	s_waitcnt lgkmcnt(6)
	v_mfma_f32_32x32x16_bf16 v[32:47], v[128:131], v[96:99], v[32:47]
	v_exp_f32_e32 v104, v104
	v_exp_f32_e32 v105, v105
	ds_read_b64_tr_b16 v[128:129], v243 offset:20480
	v_add_f32_e32 v253, v253, v104
	v_cvt_pk_bf16_f32 v104, v104, v105
	ds_read_b64_tr_b16 v[130:131], v244 offset:22528
	v_add_f32_e32 v253, v253, v105
	s_waitcnt lgkmcnt(6)
	v_mfma_f32_32x32x16_bf16 v[48:63], v[132:135], v[96:99], v[48:63]
	v_exp_f32_e32 v106, v106
	v_exp_f32_e32 v107, v107
	ds_read_b64_tr_b16 v[132:133], v245 offset:20480
	v_add_f32_e32 v253, v253, v106
	v_cvt_pk_bf16_f32 v105, v106, v107
	ds_read_b64_tr_b16 v[134:135], v246 offset:22528
	v_add_f32_e32 v253, v253, v107
	s_waitcnt lgkmcnt(6)
	v_mfma_f32_32x32x16_bf16 v[16:31], v[136:139], v[96:99], v[16:31]
	v_exp_f32_e32 v108, v108
	v_exp_f32_e32 v109, v109
	ds_read_b64_tr_b16 v[136:137], v247 offset:20480
	v_add_f32_e32 v253, v253, v108
	v_cvt_pk_bf16_f32 v106, v108, v109
	ds_read_b64_tr_b16 v[138:139], v248 offset:22528
	v_add_f32_e32 v253, v253, v109
	s_waitcnt lgkmcnt(6)
	v_mfma_f32_32x32x16_bf16 v[0:15], v[140:143], v[96:99], v[0:15]
	v_exp_f32_e32 v110, v110
	v_exp_f32_e32 v111, v111
	ds_read_b64_tr_b16 v[140:141], v249 offset:20480
	v_add_f32_e32 v253, v253, v110
	v_cvt_pk_bf16_f32 v107, v110, v111
	ds_read_b64_tr_b16 v[142:143], v250 offset:22528
	v_add_f32_e32 v253, v253, v111
	s_waitcnt lgkmcnt(6)
	v_mfma_f32_32x32x16_bf16 v[32:47], v[128:131], v[104:107], v[32:47]
	v_exp_f32_e32 v80, v80
	v_exp_f32_e32 v81, v81
	ds_read_b64_tr_b16 v[128:129], v243 offset:24576
	v_add_f32_e32 v253, v253, v80
	v_cvt_pk_bf16_f32 v80, v80, v81
	ds_read_b64_tr_b16 v[130:131], v244 offset:26624
	v_add_f32_e32 v253, v253, v81
	s_waitcnt lgkmcnt(6)
	v_mfma_f32_32x32x16_bf16 v[48:63], v[132:135], v[104:107], v[48:63]
	v_exp_f32_e32 v82, v82
	v_exp_f32_e32 v83, v83
	ds_read_b64_tr_b16 v[132:133], v245 offset:24576
	v_add_f32_e32 v253, v253, v82
	v_cvt_pk_bf16_f32 v81, v82, v83
	ds_read_b64_tr_b16 v[134:135], v246 offset:26624
	v_add_f32_e32 v253, v253, v83
	s_waitcnt lgkmcnt(6)
	v_mfma_f32_32x32x16_bf16 v[16:31], v[136:139], v[104:107], v[16:31]
	v_exp_f32_e32 v84, v84
	v_exp_f32_e32 v85, v85
	ds_read_b64_tr_b16 v[136:137], v247 offset:24576
	v_add_f32_e32 v253, v253, v84
	v_cvt_pk_bf16_f32 v82, v84, v85
	ds_read_b64_tr_b16 v[138:139], v248 offset:26624
	v_add_f32_e32 v253, v253, v85
	s_waitcnt lgkmcnt(6)
	v_mfma_f32_32x32x16_bf16 v[0:15], v[140:143], v[104:107], v[0:15]
	v_exp_f32_e32 v86, v86
	v_exp_f32_e32 v87, v87
	ds_read_b64_tr_b16 v[140:141], v249 offset:24576
	v_add_f32_e32 v253, v253, v86
	v_cvt_pk_bf16_f32 v83, v86, v87
	ds_read_b64_tr_b16 v[142:143], v250 offset:26624
	v_add_f32_e32 v253, v253, v87
	s_waitcnt lgkmcnt(6)
	v_mfma_f32_32x32x16_bf16 v[32:47], v[128:131], v[80:83], v[32:47]
	v_exp_f32_e32 v88, v88
	v_exp_f32_e32 v89, v89
	ds_read_b64_tr_b16 v[128:129], v243 offset:28672
	v_add_f32_e32 v253, v253, v88
	v_cvt_pk_bf16_f32 v88, v88, v89
	ds_read_b64_tr_b16 v[130:131], v244 offset:30720
	v_add_f32_e32 v253, v253, v89
	s_waitcnt lgkmcnt(6)
	v_mfma_f32_32x32x16_bf16 v[48:63], v[132:135], v[80:83], v[48:63]
	v_exp_f32_e32 v90, v90
	v_exp_f32_e32 v91, v91
	ds_read_b64_tr_b16 v[132:133], v245 offset:28672
	v_add_f32_e32 v253, v253, v90
	v_cvt_pk_bf16_f32 v89, v90, v91
	ds_read_b64_tr_b16 v[134:135], v246 offset:30720
	v_add_f32_e32 v253, v253, v91
	s_waitcnt lgkmcnt(6)
	v_mfma_f32_32x32x16_bf16 v[16:31], v[136:139], v[80:83], v[16:31]
	v_exp_f32_e32 v92, v92
	v_exp_f32_e32 v93, v93
	ds_read_b64_tr_b16 v[136:137], v247 offset:28672
	v_add_f32_e32 v253, v253, v92
	v_cvt_pk_bf16_f32 v90, v92, v93
	ds_read_b64_tr_b16 v[138:139], v248 offset:30720
	v_add_f32_e32 v253, v253, v93
	s_waitcnt lgkmcnt(6)
	v_mfma_f32_32x32x16_bf16 v[0:15], v[140:143], v[80:83], v[0:15]
	v_exp_f32_e32 v94, v94
	v_exp_f32_e32 v95, v95
	ds_read_b64_tr_b16 v[140:141], v249 offset:28672
	v_add_f32_e32 v253, v253, v94
	v_cvt_pk_bf16_f32 v91, v94, v95
	ds_read_b64_tr_b16 v[142:143], v250 offset:30720
	v_add_f32_e32 v253, v253, v95
	s_waitcnt lgkmcnt(6)
	v_mfma_f32_32x32x16_bf16 v[32:47], v[128:131], v[88:91], v[32:47]
	v_add_f32_e32 v156, v156, v253
	v_lshl_add_u64 v[158:159], v[158:159], 0, v[154:155]
	s_waitcnt lgkmcnt(4)
	v_mfma_f32_32x32x16_bf16 v[48:63], v[132:135], v[88:91], v[48:63]
	v_lshl_add_u64 v[160:161], v[160:161], 0, v[152:153]
	v_lshl_add_u64 v[162:163], v[162:163], 0, v[150:151]
	s_waitcnt lgkmcnt(2)
	v_mfma_f32_32x32x16_bf16 v[16:31], v[136:139], v[88:91], v[16:31]
	v_lshl_add_u64 v[164:165], v[164:165], 0, v[148:149]
	s_add_i32 s4, s4, 1
	s_add_i32 s14, s14, -1
	s_waitcnt lgkmcnt(0)
	v_mfma_f32_32x32x16_bf16 v[0:15], v[140:143], v[88:91], v[0:15]
	s_cmp_lg_u32 s5, s15
	s_cbranch_scc1 .LBB0_72
	v_and_b32_e32 v65, 64, v175
	v_xor_b32_e32 v64, 32, v175
	v_add_u32_e32 v65, 64, v65
	v_cmp_lt_i32_e32 vcc, v64, v65
	v_and_b32_e32 v65, 63, v182
	v_ashrrev_i32_e32 v120, 6, v182
	v_cndmask_b32_e32 v64, v175, v64, vcc
	v_lshlrev_b32_e32 v69, 2, v64
	ds_bpermute_b32 v64, v69, v156
	v_cmp_lt_i32_e32 vcc, 3, v120
	s_barrier
; DEV void attn_diff_unit(const Params& p, int l, int bl, int hd, int q_t0, int n_tiles, char* smem) {
;     ...
;   float* xb = (float*)smem;
;   if (w >= 4) {
; #pragma unroll
;     for (int v = 0; v < 4; ++v)
; #pragma unroll
;       for (int e = 0; e < 16; ++e) xb[((w - 4) * 64 + v * 16 + e) * 64 + lane] = o[v][e] * linv;
;   }
	s_waitcnt lgkmcnt(0)
	v_add_f32_e32 v64, v156, v64
	v_rcp_f32_e32 v68, v64
	v_lshlrev_b32_e32 v64, 2, v65
	v_lshlrev_b32_e32 v65, 8, v182
	v_and_b32_e32 v65, 0xffffc000, v65
	s_and_saveexec_b64 s[0:1], vcc
	s_cbranch_execz .LBB0_93
	v_add3_u32 v67, 0, v64, v65
	v_mul_f32_e32 v66, v32, v68
	v_add_u32_e32 v70, 0xffff0000, v67
	ds_write_b32 v70, v66
	v_mul_f32_e32 v66, v33, v68
	v_add_u32_e32 v70, 0xffff0100, v67
	ds_write_b32 v70, v66
	v_mul_f32_e32 v66, v34, v68
	v_add_u32_e32 v70, 0xffff0200, v67
	ds_write_b32 v70, v66
	v_mul_f32_e32 v66, v35, v68
	v_add_u32_e32 v70, 0xffff0300, v67
	ds_write_b32 v70, v66
	v_mul_f32_e32 v66, v36, v68
	v_add_u32_e32 v70, 0xffff0400, v67
	ds_write_b32 v70, v66
	v_mul_f32_e32 v66, v37, v68
	v_add_u32_e32 v70, 0xffff0500, v67
	ds_write_b32 v70, v66
	v_mul_f32_e32 v66, v38, v68
	v_add_u32_e32 v70, 0xffff0600, v67
	ds_write_b32 v70, v66
	v_mul_f32_e32 v66, v39, v68
	v_add_u32_e32 v70, 0xffff0700, v67
	ds_write_b32 v70, v66
	v_mul_f32_e32 v66, v40, v68
	v_add_u32_e32 v70, 0xffff0800, v67
	ds_write_b32 v70, v66
	v_mul_f32_e32 v66, v41, v68
	v_add_u32_e32 v70, 0xffff0900, v67
	ds_write_b32 v70, v66
	v_mul_f32_e32 v66, v42, v68
	v_add_u32_e32 v70, 0xffff0a00, v67
	ds_write_b32 v70, v66
	v_mul_f32_e32 v66, v43, v68
	v_add_u32_e32 v70, 0xffff0b00, v67
	ds_write_b32 v70, v66
	v_mul_f32_e32 v66, v44, v68
	v_add_u32_e32 v70, 0xffff0c00, v67
	ds_write_b32 v70, v66
	v_mul_f32_e32 v66, v45, v68
	v_add_u32_e32 v70, 0xffff0d00, v67
	ds_write_b32 v70, v66
	v_mul_f32_e32 v66, v46, v68
	v_add_u32_e32 v70, 0xffff0e00, v67
	ds_write_b32 v70, v66
	v_mul_f32_e32 v66, v47, v68
	v_add_u32_e32 v70, 0xffff0f00, v67
	ds_write_b32 v70, v66
	v_mul_f32_e32 v66, v48, v68
	v_add_u32_e32 v70, 0xffff1000, v67
	ds_write_b32 v70, v66
	v_mul_f32_e32 v66, v49, v68
	v_add_u32_e32 v70, 0xffff1100, v67
	ds_write_b32 v70, v66
	v_mul_f32_e32 v66, v50, v68
	v_add_u32_e32 v70, 0xffff1200, v67
	ds_write_b32 v70, v66
	v_mul_f32_e32 v66, v51, v68
	v_add_u32_e32 v70, 0xffff1300, v67
	ds_write_b32 v70, v66
	v_mul_f32_e32 v66, v52, v68
	v_add_u32_e32 v70, 0xffff1400, v67
	ds_write_b32 v70, v66
	v_mul_f32_e32 v66, v53, v68
	v_add_u32_e32 v70, 0xffff1500, v67
	ds_write_b32 v70, v66
	v_mul_f32_e32 v66, v54, v68
	v_add_u32_e32 v70, 0xffff1600, v67
	ds_write_b32 v70, v66
	v_mul_f32_e32 v66, v55, v68
	v_add_u32_e32 v70, 0xffff1700, v67
	ds_write_b32 v70, v66
	v_mul_f32_e32 v66, v56, v68
	v_add_u32_e32 v70, 0xffff1800, v67
	ds_write_b32 v70, v66
	v_mul_f32_e32 v66, v57, v68
	v_add_u32_e32 v70, 0xffff1900, v67
	ds_write_b32 v70, v66
	v_mul_f32_e32 v66, v58, v68
	v_add_u32_e32 v70, 0xffff1a00, v67
	ds_write_b32 v70, v66
	v_mul_f32_e32 v66, v59, v68
	v_add_u32_e32 v70, 0xffff1b00, v67
	ds_write_b32 v70, v66
	v_mul_f32_e32 v66, v60, v68
	v_add_u32_e32 v70, 0xffff1c00, v67
	ds_write_b32 v70, v66
	v_mul_f32_e32 v66, v61, v68
	v_add_u32_e32 v70, 0xffff1d00, v67
	ds_write_b32 v70, v66
	v_mul_f32_e32 v66, v62, v68
	v_add_u32_e32 v70, 0xffff1e00, v67
	ds_write_b32 v70, v66
	v_mul_f32_e32 v66, v63, v68
	v_add_u32_e32 v70, 0xffff1f00, v67
	ds_write_b32 v70, v66
	v_mul_f32_e32 v66, v16, v68
	v_add_u32_e32 v70, 0xffff2000, v67
	ds_write_b32 v70, v66
	v_mul_f32_e32 v66, v17, v68
	v_add_u32_e32 v70, 0xffff2100, v67
	ds_write_b32 v70, v66
	v_mul_f32_e32 v66, v18, v68
	v_add_u32_e32 v70, 0xffff2200, v67
	ds_write_b32 v70, v66
	v_mul_f32_e32 v66, v19, v68
	v_add_u32_e32 v70, 0xffff2300, v67
	ds_write_b32 v70, v66
	v_mul_f32_e32 v66, v20, v68
	v_add_u32_e32 v70, 0xffff2400, v67
	ds_write_b32 v70, v66
	v_mul_f32_e32 v66, v21, v68
	v_add_u32_e32 v70, 0xffff2500, v67
	ds_write_b32 v70, v66
	v_mul_f32_e32 v66, v22, v68
	v_add_u32_e32 v70, 0xffff2600, v67
	ds_write_b32 v70, v66
	v_mul_f32_e32 v66, v23, v68
	v_add_u32_e32 v70, 0xffff2700, v67
	ds_write_b32 v70, v66
	v_mul_f32_e32 v66, v24, v68
	v_add_u32_e32 v70, 0xffff2800, v67
	ds_write_b32 v70, v66
	v_mul_f32_e32 v66, v25, v68
	v_add_u32_e32 v70, 0xffff2900, v67
	ds_write_b32 v70, v66
	v_mul_f32_e32 v66, v26, v68
	v_add_u32_e32 v70, 0xffff2a00, v67
	ds_write_b32 v70, v66
	v_mul_f32_e32 v66, v27, v68
	v_add_u32_e32 v70, 0xffff2b00, v67
	ds_write_b32 v70, v66
	v_mul_f32_e32 v66, v28, v68
	v_add_u32_e32 v70, 0xffff2c00, v67
	ds_write_b32 v70, v66
	v_mul_f32_e32 v66, v29, v68
	v_add_u32_e32 v70, 0xffff2d00, v67
	ds_write_b32 v70, v66
	v_mul_f32_e32 v66, v30, v68
	v_add_u32_e32 v70, 0xffff2e00, v67
	ds_write_b32 v70, v66
	v_mul_f32_e32 v66, v31, v68
	v_add_u32_e32 v70, 0xffff2f00, v67
	ds_write_b32 v70, v66
	v_mul_f32_e32 v66, v0, v68
	v_add_u32_e32 v70, 0xffff3000, v67
	ds_write_b32 v70, v66
	v_mul_f32_e32 v66, v1, v68
	v_add_u32_e32 v70, 0xffff3100, v67
	ds_write_b32 v70, v66
	v_mul_f32_e32 v66, v2, v68
	v_add_u32_e32 v70, 0xffff3200, v67
	ds_write_b32 v70, v66
	v_mul_f32_e32 v66, v3, v68
	v_add_u32_e32 v70, 0xffff3300, v67
	ds_write_b32 v70, v66
	v_mul_f32_e32 v66, v4, v68
	v_add_u32_e32 v70, 0xffff3400, v67
	ds_write_b32 v70, v66
	v_mul_f32_e32 v66, v5, v68
	v_add_u32_e32 v70, 0xffff3500, v67
	ds_write_b32 v70, v66
	v_mul_f32_e32 v66, v6, v68
	v_add_u32_e32 v70, 0xffff3600, v67
	ds_write_b32 v70, v66
	v_mul_f32_e32 v66, v7, v68
	v_add_u32_e32 v70, 0xffff3700, v67
	ds_write_b32 v70, v66
	v_mul_f32_e32 v66, v8, v68
	v_add_u32_e32 v70, 0xffff3800, v67
	ds_write_b32 v70, v66
	v_mul_f32_e32 v66, v9, v68
	v_add_u32_e32 v70, 0xffff3900, v67
	ds_write_b32 v70, v66
	v_mul_f32_e32 v66, v10, v68
	v_add_u32_e32 v70, 0xffff3a00, v67
	ds_write_b32 v70, v66
	v_mul_f32_e32 v66, v11, v68
	v_add_u32_e32 v70, 0xffff3b00, v67
	ds_write_b32 v70, v66
	v_mul_f32_e32 v66, v12, v68
	v_add_u32_e32 v70, 0xffff3c00, v67
	ds_write_b32 v70, v66
	v_mul_f32_e32 v66, v13, v68
	v_add_u32_e32 v70, 0xffff3d00, v67
	ds_write_b32 v70, v66
	v_mul_f32_e32 v66, v14, v68
	v_add_u32_e32 v70, 0xffff3e00, v67
	ds_write_b32 v70, v66
	v_mul_f32_e32 v66, v15, v68
	v_add_u32_e32 v67, 0xffff3f00, v67
	ds_write_b32 v67, v66

; #define LAS __attribute__((address_space(3)))
; DEV unsigned xb_add(unsigned* p, unsigned v) { return __hip_atomic_fetch_add(p, v, __ATOMIC_RELAXED, __HIP_MEMORY_SCOPE_AGENT); }
; DEV unsigned xb_xcc_id() { return (unsigned)__builtin_amdgcn_s_getreg((3 << 11) | 20) & 0xFu; }
; __global__ void __launch_bounds__(512) mega_kernel(Params p, int ph_begin, int ph_end) {
;   extern __shared__ __attribute__((aligned(16))) char smem[];
;   volatile LAS unsigned* st = (volatile LAS unsigned*)(smem + SMEM_BYTES);
;   unsigned* bar = (unsigned*)(p.ws + OFF_BAR);
;   if (threadIdx.x < 2) st[threadIdx.x] = 0u;
;   __syncthreads();
;   const unsigned xcc = xb_xcc_id();
;   if (threadIdx.x == 0) (void)xb_add(&bar[XB_XCNT(xcc)], 1u);
;   for (int ph = ph_begin; ph < ph_end; ++ph) {
;     run_phase(p, ph, smem);
;     if (ph + 1 < ph_end) {
;       if (ph == ph_begin) cg::this_grid().sync();
;       else xcd_barrier(bar, xcc, st);
;     }
;   }
; }
	.amdhsa_kernel _Z11mega_kernel6Paramsii
		.amdhsa_group_segment_fixed_size 0
		.amdhsa_private_segment_fixed_size 0
		.amdhsa_kernarg_size 488
		.amdhsa_user_sgpr_count 2
		.amdhsa_user_sgpr_dispatch_ptr 0
		.amdhsa_user_sgpr_queue_ptr 0
		.amdhsa_user_sgpr_kernarg_segment_ptr 1
		.amdhsa_user_sgpr_dispatch_id 0
		.amdhsa_user_sgpr_kernarg_preload_length 0
		.amdhsa_user_sgpr_kernarg_preload_offset 0
		.amdhsa_user_sgpr_private_segment_size 0
		.amdhsa_uses_dynamic_stack 0
		.amdhsa_enable_private_segment 0
		.amdhsa_system_sgpr_workgroup_id_x 1
		.amdhsa_system_sgpr_workgroup_id_y 0
		.amdhsa_system_sgpr_workgroup_id_z 0
		.amdhsa_system_sgpr_workgroup_info 0
		.amdhsa_system_vgpr_workitem_id 2
		.amdhsa_next_free_vgpr 256
		.amdhsa_next_free_sgpr 98
		.amdhsa_accum_offset 256
		.amdhsa_reserve_vcc 1
		.amdhsa_float_round_mode_32 0
		.amdhsa_float_round_mode_16_64 0
		.amdhsa_float_denorm_mode_32 3
		.amdhsa_float_denorm_mode_16_64 3
		.amdhsa_dx10_clamp 1
		.amdhsa_ieee_mode 1
		.amdhsa_fp16_overflow 0
		.amdhsa_tg_split 0
		.amdhsa_exception_fp_ieee_invalid_op 0
		.amdhsa_exception_fp_denorm_src 0
		.amdhsa_exception_fp_ieee_div_zero 0
		.amdhsa_exception_fp_ieee_overflow 0
		.amdhsa_exception_fp_ieee_underflow 0
		.amdhsa_exception_fp_ieee_inexact 0
		.amdhsa_exception_int_div_zero 0
	.end_amdhsa_kernel

; #define LAS __attribute__((address_space(3)))
; DEV unsigned xb_add(unsigned* p, unsigned v) { return __hip_atomic_fetch_add(p, v, __ATOMIC_RELAXED, __HIP_MEMORY_SCOPE_AGENT); }
; DEV unsigned xb_xcc_id() { return (unsigned)__builtin_amdgcn_s_getreg((3 << 11) | 20) & 0xFu; }
; __global__ void __launch_bounds__(512) mega_kernel(Params p, int ph_begin, int ph_end) {
;   extern __shared__ __attribute__((aligned(16))) char smem[];
;   volatile LAS unsigned* st = (volatile LAS unsigned*)(smem + SMEM_BYTES);
;   unsigned* bar = (unsigned*)(p.ws + OFF_BAR);
;   if (threadIdx.x < 2) st[threadIdx.x] = 0u;
;   __syncthreads();
;   const unsigned xcc = xb_xcc_id();
;   if (threadIdx.x == 0) (void)xb_add(&bar[XB_XCNT(xcc)], 1u);
;   for (int ph = ph_begin; ph < ph_end; ++ph) {
;     run_phase(p, ph, smem);
;     if (ph + 1 < ph_end) {
;       if (ph == ph_begin) cg::this_grid().sync();
;       else xcd_barrier(bar, xcc, st);
;     }
;   }
; }
amdhsa.kernels:
  - .agpr_count:     0
    .args:
      - .offset:         0
        .size:           224
        .value_kind:     by_value
      - .offset:         224
        .size:           4
        .value_kind:     by_value
      - .offset:         228
        .size:           4
        .value_kind:     by_value
      - .offset:         232
        .size:           4
        .value_kind:     hidden_block_count_x
      - .offset:         236
        .size:           4
        .value_kind:     hidden_block_count_y
      - .offset:         240
        .size:           4
        .value_kind:     hidden_block_count_z
      - .offset:         244
        .size:           2
        .value_kind:     hidden_group_size_x
      - .offset:         246
        .size:           2
        .value_kind:     hidden_group_size_y
      - .offset:         248
        .size:           2
        .value_kind:     hidden_group_size_z
      - .offset:         250
        .size:           2
        .value_kind:     hidden_remainder_x
      - .offset:         252
        .size:           2
        .value_kind:     hidden_remainder_y
      - .offset:         254
        .size:           2
        .value_kind:     hidden_remainder_z
      - .offset:         272
        .size:           8
        .value_kind:     hidden_global_offset_x
      - .offset:         280
        .size:           8
        .value_kind:     hidden_global_offset_y
      - .offset:         288
        .size:           8
        .value_kind:     hidden_global_offset_z
      - .offset:         296
        .size:           2
        .value_kind:     hidden_grid_dims
      - .offset:         320
        .size:           8
        .value_kind:     hidden_multigrid_sync_arg
      - .offset:         352
        .size:           4
        .value_kind:     hidden_dynamic_lds_size
    .group_segment_fixed_size: 0
    .kernarg_segment_align: 8
    .kernarg_segment_size: 488
    .language:       OpenCL C
    .language_version:
      - 2
      - 0
    .max_flat_workgroup_size: 512
    .name:           _Z11mega_kernel6Paramsii
    .private_segment_fixed_size: 0
    .sgpr_count:     104
    .sgpr_spill_count: 202
    .symbol:         _Z11mega_kernel6Paramsii.kd
    .uniform_work_group_size: 1
    .uses_dynamic_stack: false
    .vgpr_count:     256
    .vgpr_spill_count: 0
    .wavefront_size: 64
